# M8 scalar bookkeeping fully inside the MFMA block (P2,P9)
# baseline (speedup 1.0000x reference)
; #define PG8_STAGE(bufoff, gbase) PG8_STAGE_(bufoff, gbase, voffA)
; #define PG8_STAGEB(bufoff, gbase) PG8_STAGE_(bufoff, gbase, voffB)
; #define PG8_LDA(dst, b, h) do { _Pragma("unroll") for (int m = 0; m < 4; ++m) _Pragma("unroll") for (int k = 0; k < 2; ++k) dst[m][k] = *(const LAS bf16x8*)(lds + PG8_SA(b, h) + aoff + m * 2048 + k * 1024); } while (0)
; #define PG8_LDB(dst, b, h) do { _Pragma("unroll") for (int n = 0; n < 2; ++n) _Pragma("unroll") for (int k = 0; k < 2; ++k) dst[n][k] = *(const LAS bf16x8*)(lds + PG8_SB(b, h) + boff + n * 2048 + k * 1024); } while (0)
; #define PG8_MMA(ai, bj, At, Bt) do { __builtin_amdgcn_s_setprio(1); _Pragma("unroll") for (int m = 0; m < 4; ++m) _Pragma("unroll") for (int n = 0; n < 2; ++n) _Pragma("unroll") for (int k = 0; k < 2; ++k) \
;         acc[ai][bj][m][n] = __builtin_amdgcn_mfma_f32_16x16x32_bf16(Bt[n][k], At[m][k], acc[ai][bj][m][n], 0, 0, 0); __builtin_amdgcn_s_setprio(0); } while (0)
; #define PG8_WAIT_V(n) asm volatile("s_waitcnt vmcnt(" #n ")" ::: "memory")
; #define PG8_WAIT_L(n) asm volatile("s_waitcnt lgkmcnt(" #n ")" ::: "memory")
; #define PG8_BAR __builtin_amdgcn_s_barrier()
; #define PG8_SCHED __builtin_amdgcn_sched_barrier(0)
; template <class Epi>
; __device__ __forceinline__ void gemm_phase(LAS unsigned char* lds, const Gemm g, const StaticOrder& S, const Epi& E) {
;     ...
;             PG8_LDB(B0, 0, 0); PG8_SCHED; PG8_LDA(At, 0, 0); PG8_STAGE(PG8_SA(1, 1), a1 + hstep);
;             PG8_WAIT_L(8); PG8_BAR; PG8_WAIT_L(0); PG8_MMA(0, 0, At, B0); PG8_BAR; PG8_SCHED;
;             PG8_LDB(B1, 0, 1); PG8_STAGEB(PG8_SB(0, 0), b2);
;             PG8_BAR; PG8_WAIT_L(0); PG8_MMA(0, 1, At, B1); PG8_BAR;
;             PG8_LDA(At, 0, 1); PG8_STAGE(PG8_SA(0, 0), a2);
;             PG8_BAR; PG8_WAIT_L(0); PG8_MMA(1, 0, At, B0); PG8_BAR; PG8_SCHED;
;             PG8_STAGEB(PG8_SB(0, 1), b2 + hstep);
;             PG8_WAIT_V(6); PG8_BAR; PG8_MMA(1, 1, At, B1); PG8_BAR;
;             PG8_LDB(B0, 1, 0); PG8_SCHED; PG8_LDA(At, 1, 0); PG8_STAGE(PG8_SA(0, 1), a2 + hstep);
;             PG8_WAIT_L(8); PG8_BAR; PG8_WAIT_L(0); PG8_MMA(0, 0, At, B0); PG8_BAR; PG8_SCHED;
.LBB0_426:
	ds_read_b128 v[74:77], v148
	ds_read_b128 v[86:89], v148 offset:1024
	ds_read_b128 v[90:93], v148 offset:2048
	ds_read_b128 v[94:97], v148 offset:3072
	ds_read_b128 v[166:169], v171
	ds_read_b128 v[172:175], v171 offset:1024
	ds_read_b128 v[176:179], v171 offset:2048
	ds_read_b128 v[206:209], v171 offset:3072
	ds_read_b128 v[210:213], v171 offset:4096
	ds_read_b128 v[214:217], v171 offset:5120
	ds_read_b128 v[218:221], v171 offset:6144
	global_load_lds_dwordx4 v162, s[30:31]
	s_add_i32 m0, s62, 0xe000
	ds_read_b128 v[222:225], v171 offset:7168
	global_load_lds_dwordx4 v164, s[30:31]
	s_waitcnt lgkmcnt(8)
	s_barrier
	s_waitcnt lgkmcnt(0)
	s_setprio 1
	v_mfma_f32_16x16x32_bf16 v[138:141], v[74:77], v[166:169], v[138:141]
	v_mfma_f32_16x16x32_bf16 v[142:145], v[90:93], v[166:169], v[142:145]
	s_add_i32 s59, 0, 0x14000
	v_mfma_f32_16x16x32_bf16 v[122:125], v[74:77], v[176:179], v[122:125]
	s_add_i32 s58, s58, s55
	v_mfma_f32_16x16x32_bf16 v[126:129], v[90:93], v[176:179], v[126:129]
	s_mov_b32 m0, s58
	v_mfma_f32_16x16x32_bf16 v[106:109], v[74:77], v[210:213], v[106:109]
	v_mfma_f32_16x16x32_bf16 v[110:113], v[90:93], v[210:213], v[110:113]
	v_mfma_f32_16x16x32_bf16 v[78:81], v[74:77], v[218:221], v[78:81]
	v_mfma_f32_16x16x32_bf16 v[82:85], v[90:93], v[218:221], v[82:85]
	v_mfma_f32_16x16x32_bf16 v[138:141], v[86:89], v[172:175], v[138:141]
	v_mfma_f32_16x16x32_bf16 v[142:145], v[94:97], v[172:175], v[142:145]
	v_mfma_f32_16x16x32_bf16 v[122:125], v[86:89], v[206:209], v[122:125]
	v_mfma_f32_16x16x32_bf16 v[126:129], v[94:97], v[206:209], v[126:129]
	v_mfma_f32_16x16x32_bf16 v[106:109], v[86:89], v[214:217], v[106:109]
	v_mfma_f32_16x16x32_bf16 v[110:113], v[94:97], v[214:217], v[110:113]
	v_mfma_f32_16x16x32_bf16 v[78:81], v[86:89], v[222:225], v[78:81]
	v_mfma_f32_16x16x32_bf16 v[82:85], v[94:97], v[222:225], v[82:85]
	s_setprio 0
	s_barrier
	ds_read_b128 v[226:229], v149
	ds_read_b128 v[230:233], v149 offset:1024
	ds_read_b128 v[234:237], v149 offset:2048
	global_load_lds_dwordx4 v0, s[20:21]
	s_add_i32 m0, s58, 0x2000
	ds_read_b128 v[238:241], v149 offset:3072
	global_load_lds_dwordx4 v156, s[20:21]
	s_barrier
	s_waitcnt lgkmcnt(0)
	s_setprio 1
	v_mfma_f32_16x16x32_bf16 v[130:133], v[226:229], v[166:169], v[130:133]
	v_mfma_f32_16x16x32_bf16 v[134:137], v[234:237], v[166:169], v[134:137]
	v_mfma_f32_16x16x32_bf16 v[114:117], v[226:229], v[176:179], v[114:117]
	v_mfma_f32_16x16x32_bf16 v[118:121], v[234:237], v[176:179], v[118:121]
	v_mfma_f32_16x16x32_bf16 v[98:101], v[226:229], v[210:213], v[98:101]
	v_mfma_f32_16x16x32_bf16 v[102:105], v[234:237], v[210:213], v[102:105]
	v_mfma_f32_16x16x32_bf16 v[66:69], v[226:229], v[218:221], v[66:69]
	v_mfma_f32_16x16x32_bf16 v[70:73], v[234:237], v[218:221], v[70:73]
	v_mfma_f32_16x16x32_bf16 v[130:133], v[230:233], v[172:175], v[130:133]
	v_mfma_f32_16x16x32_bf16 v[134:137], v[238:241], v[172:175], v[134:137]
	v_mfma_f32_16x16x32_bf16 v[114:117], v[230:233], v[206:209], v[114:117]
	v_mfma_f32_16x16x32_bf16 v[118:121], v[238:241], v[206:209], v[118:121]
	v_mfma_f32_16x16x32_bf16 v[98:101], v[230:233], v[214:217], v[98:101]
	v_mfma_f32_16x16x32_bf16 v[102:105], v[238:241], v[214:217], v[102:105]
	v_mfma_f32_16x16x32_bf16 v[66:69], v[230:233], v[222:225], v[66:69]
	v_mfma_f32_16x16x32_bf16 v[70:73], v[238:241], v[222:225], v[70:73]
	s_setprio 0
	s_mov_b32 m0, s62
	s_barrier
	ds_read_b128 v[166:169], v171 offset:16384
	ds_read_b128 v[172:175], v171 offset:17408
	ds_read_b128 v[176:179], v171 offset:18432
	ds_read_b128 v[206:209], v171 offset:19456
	ds_read_b128 v[210:213], v171 offset:20480
	ds_read_b128 v[214:217], v171 offset:21504
	ds_read_b128 v[218:221], v171 offset:22528
	global_load_lds_dwordx4 v160, s[44:45]
	s_mov_b32 m0, s63
	ds_read_b128 v[222:225], v171 offset:23552
	global_load_lds_dwordx4 v158, s[44:45]
	s_barrier
	s_waitcnt lgkmcnt(0)
	s_setprio 1
	v_mfma_f32_16x16x32_bf16 v[58:61], v[74:77], v[166:169], v[58:61]
	v_mfma_f32_16x16x32_bf16 v[62:65], v[90:93], v[166:169], v[62:65]
	s_add_u32 s90, s20, 0x80000
	v_mfma_f32_16x16x32_bf16 v[42:45], v[74:77], v[176:179], v[42:45]
	s_addc_u32 s91, s21, 0
	v_mfma_f32_16x16x32_bf16 v[46:49], v[90:93], v[176:179], v[46:49]
	s_add_i32 s58, s59, s55
	v_mfma_f32_16x16x32_bf16 v[26:29], v[74:77], v[210:213], v[26:29]
	s_mov_b32 m0, s58
	v_mfma_f32_16x16x32_bf16 v[30:33], v[90:93], v[210:213], v[30:33]
	v_mfma_f32_16x16x32_bf16 v[10:13], v[74:77], v[218:221], v[10:13]
	v_mfma_f32_16x16x32_bf16 v[14:17], v[90:93], v[218:221], v[14:17]
	v_mfma_f32_16x16x32_bf16 v[58:61], v[86:89], v[172:175], v[58:61]
	v_mfma_f32_16x16x32_bf16 v[62:65], v[94:97], v[172:175], v[62:65]
	v_mfma_f32_16x16x32_bf16 v[42:45], v[86:89], v[206:209], v[42:45]
	v_mfma_f32_16x16x32_bf16 v[46:49], v[94:97], v[206:209], v[46:49]
	v_mfma_f32_16x16x32_bf16 v[26:29], v[86:89], v[214:217], v[26:29]
	v_mfma_f32_16x16x32_bf16 v[30:33], v[94:97], v[214:217], v[30:33]
	v_mfma_f32_16x16x32_bf16 v[10:13], v[86:89], v[222:225], v[10:13]
	v_mfma_f32_16x16x32_bf16 v[14:17], v[94:97], v[222:225], v[14:17]
	s_setprio 0
	s_barrier
	global_load_lds_dwordx4 v0, s[90:91]
	s_add_i32 m0, s58, 0x2000
	s_nop 0
	global_load_lds_dwordx4 v156, s[90:91]
	s_waitcnt vmcnt(6)
	s_barrier
; #define PG8_STAGE(bufoff, gbase) PG8_STAGE_(bufoff, gbase, voffA)
; #define PG8_STAGEB(bufoff, gbase) PG8_STAGE_(bufoff, gbase, voffB)
; #define PG8_LDA(dst, b, h) do { _Pragma("unroll") for (int m = 0; m < 4; ++m) _Pragma("unroll") for (int k = 0; k < 2; ++k) dst[m][k] = *(const LAS bf16x8*)(lds + PG8_SA(b, h) + aoff + m * 2048 + k * 1024); } while (0)
; #define PG8_LDB(dst, b, h) do { _Pragma("unroll") for (int n = 0; n < 2; ++n) _Pragma("unroll") for (int k = 0; k < 2; ++k) dst[n][k] = *(const LAS bf16x8*)(lds + PG8_SB(b, h) + boff + n * 2048 + k * 1024); } while (0)
; #define PG8_MMA(ai, bj, At, Bt) do { __builtin_amdgcn_s_setprio(1); _Pragma("unroll") for (int m = 0; m < 4; ++m) _Pragma("unroll") for (int n = 0; n < 2; ++n) _Pragma("unroll") for (int k = 0; k < 2; ++k) \
;         acc[ai][bj][m][n] = __builtin_amdgcn_mfma_f32_16x16x32_bf16(Bt[n][k], At[m][k], acc[ai][bj][m][n], 0, 0, 0); __builtin_amdgcn_s_setprio(0); } while (0)
; #define PG8_WAIT_V(n) asm volatile("s_waitcnt vmcnt(" #n ")" ::: "memory")
; #define PG8_WAIT_L(n) asm volatile("s_waitcnt lgkmcnt(" #n ")" ::: "memory")
; #define PG8_BAR __builtin_amdgcn_s_barrier()
; #define PG8_SCHED __builtin_amdgcn_sched_barrier(0)
; template <class Epi>
; __device__ __forceinline__ void gemm_phase(LAS unsigned char* lds, const Gemm g, const StaticOrder& S, const Epi& E) {
;     ...
;             PG8_WAIT_V(6); PG8_BAR; PG8_MMA(1, 1, At, B1); PG8_BAR;
;             PG8_LDB(B0, 1, 0); PG8_SCHED; PG8_LDA(At, 1, 0); PG8_STAGE(PG8_SA(0, 1), a2 + hstep);
;             PG8_WAIT_L(8); PG8_BAR; PG8_WAIT_L(0); PG8_MMA(0, 0, At, B0); PG8_BAR; PG8_SCHED;
;             PG8_LDB(B1, 1, 1); PG8_STAGEB(PG8_SB(1, 0), b3);
;             PG8_BAR; PG8_WAIT_L(0); PG8_MMA(0, 1, At, B1); PG8_BAR;
;             PG8_LDA(At, 1, 1); PG8_STAGE(PG8_SA(1, 0), a3);
;             PG8_BAR; PG8_WAIT_L(0); PG8_MMA(1, 0, At, B0); PG8_BAR; PG8_SCHED;
	s_setprio 1
	v_mfma_f32_16x16x32_bf16 v[50:53], v[226:229], v[166:169], v[50:53]
	v_mfma_f32_16x16x32_bf16 v[54:57], v[234:237], v[166:169], v[54:57]
	s_add_i32 s58, 0, 0x18000
	v_mfma_f32_16x16x32_bf16 v[34:37], v[226:229], v[176:179], v[34:37]
	s_add_u32 s44, s44, 0x80000
	v_mfma_f32_16x16x32_bf16 v[38:41], v[234:237], v[176:179], v[38:41]
	s_addc_u32 s45, s45, 0
	v_mfma_f32_16x16x32_bf16 v[18:21], v[226:229], v[210:213], v[18:21]
	s_mov_b32 m0, s66
	v_mfma_f32_16x16x32_bf16 v[22:25], v[234:237], v[210:213], v[22:25]
	s_add_u32 s90, s20, s16
	v_mfma_f32_16x16x32_bf16 v[6:9], v[226:229], v[218:221], v[6:9]
	s_addc_u32 s91, s21, s17
	v_mfma_f32_16x16x32_bf16 v[2:5], v[234:237], v[218:221], v[2:5]
	v_mfma_f32_16x16x32_bf16 v[50:53], v[230:233], v[172:175], v[50:53]
	v_mfma_f32_16x16x32_bf16 v[54:57], v[238:241], v[172:175], v[54:57]
	v_mfma_f32_16x16x32_bf16 v[34:37], v[230:233], v[206:209], v[34:37]
	v_mfma_f32_16x16x32_bf16 v[38:41], v[238:241], v[206:209], v[38:41]
	v_mfma_f32_16x16x32_bf16 v[18:21], v[230:233], v[214:217], v[18:21]
	v_mfma_f32_16x16x32_bf16 v[22:25], v[238:241], v[214:217], v[22:25]
	v_mfma_f32_16x16x32_bf16 v[6:9], v[230:233], v[222:225], v[6:9]
	v_mfma_f32_16x16x32_bf16 v[2:5], v[238:241], v[222:225], v[2:5]
	s_setprio 0
	s_barrier
	ds_read_b128 v[74:77], v150
	ds_read_b128 v[86:89], v150 offset:1024
	ds_read_b128 v[90:93], v150 offset:2048
	ds_read_b128 v[94:97], v150 offset:3072
	ds_read_b128 v[166:169], v171 offset:32768
	ds_read_b128 v[172:175], v171 offset:33792
	ds_read_b128 v[176:179], v171 offset:34816
	ds_read_b128 v[206:209], v171 offset:35840
	ds_read_b128 v[210:213], v171 offset:36864
	ds_read_b128 v[214:217], v171 offset:37888
	ds_read_b128 v[218:221], v171 offset:38912
	global_load_lds_dwordx4 v160, s[44:45]
	s_mov_b32 m0, s67
	ds_read_b128 v[222:225], v171 offset:39936
	global_load_lds_dwordx4 v158, s[44:45]
	s_waitcnt lgkmcnt(8)
	s_barrier
	s_waitcnt lgkmcnt(0)
	s_setprio 1
	v_mfma_f32_16x16x32_bf16 v[138:141], v[74:77], v[166:169], v[138:141]
	v_mfma_f32_16x16x32_bf16 v[142:145], v[90:93], v[166:169], v[142:145]
	s_add_i32 s44, 0, 0x1c000
	v_mfma_f32_16x16x32_bf16 v[122:125], v[74:77], v[176:179], v[122:125]
	s_add_i32 s45, s58, s55
	v_mfma_f32_16x16x32_bf16 v[126:129], v[90:93], v[176:179], v[126:129]
	s_mov_b32 m0, s45
	v_mfma_f32_16x16x32_bf16 v[106:109], v[74:77], v[210:213], v[106:109]
	v_mfma_f32_16x16x32_bf16 v[110:113], v[90:93], v[210:213], v[110:113]
	v_mfma_f32_16x16x32_bf16 v[78:81], v[74:77], v[218:221], v[78:81]
	v_mfma_f32_16x16x32_bf16 v[82:85], v[90:93], v[218:221], v[82:85]
	v_mfma_f32_16x16x32_bf16 v[138:141], v[86:89], v[172:175], v[138:141]
	v_mfma_f32_16x16x32_bf16 v[142:145], v[94:97], v[172:175], v[142:145]
	v_mfma_f32_16x16x32_bf16 v[122:125], v[86:89], v[206:209], v[122:125]
	v_mfma_f32_16x16x32_bf16 v[126:129], v[94:97], v[206:209], v[126:129]
	v_mfma_f32_16x16x32_bf16 v[106:109], v[86:89], v[214:217], v[106:109]
	v_mfma_f32_16x16x32_bf16 v[110:113], v[94:97], v[214:217], v[110:113]
	v_mfma_f32_16x16x32_bf16 v[78:81], v[86:89], v[222:225], v[78:81]
	v_mfma_f32_16x16x32_bf16 v[82:85], v[94:97], v[222:225], v[82:85]
	s_setprio 0
	s_barrier
	ds_read_b128 v[226:229], v151
	ds_read_b128 v[230:233], v151 offset:1024
	ds_read_b128 v[234:237], v151 offset:2048
	global_load_lds_dwordx4 v0, s[90:91]
	s_add_i32 m0, s45, 0x2000
	ds_read_b128 v[238:241], v151 offset:3072
	global_load_lds_dwordx4 v156, s[90:91]
	s_barrier
	s_waitcnt lgkmcnt(0)
	s_setprio 1
	v_mfma_f32_16x16x32_bf16 v[130:133], v[226:229], v[166:169], v[130:133]
	v_mfma_f32_16x16x32_bf16 v[134:137], v[234:237], v[166:169], v[134:137]
	v_mfma_f32_16x16x32_bf16 v[114:117], v[226:229], v[176:179], v[114:117]
	v_mfma_f32_16x16x32_bf16 v[118:121], v[234:237], v[176:179], v[118:121]
	v_mfma_f32_16x16x32_bf16 v[98:101], v[226:229], v[210:213], v[98:101]
	v_mfma_f32_16x16x32_bf16 v[102:105], v[234:237], v[210:213], v[102:105]
	v_mfma_f32_16x16x32_bf16 v[66:69], v[226:229], v[218:221], v[66:69]
	v_mfma_f32_16x16x32_bf16 v[70:73], v[234:237], v[218:221], v[70:73]
	v_mfma_f32_16x16x32_bf16 v[130:133], v[230:233], v[172:175], v[130:133]
	v_mfma_f32_16x16x32_bf16 v[134:137], v[238:241], v[172:175], v[134:137]
	v_mfma_f32_16x16x32_bf16 v[114:117], v[230:233], v[206:209], v[114:117]
	v_mfma_f32_16x16x32_bf16 v[118:121], v[238:241], v[206:209], v[118:121]
	v_mfma_f32_16x16x32_bf16 v[98:101], v[230:233], v[214:217], v[98:101]
	v_mfma_f32_16x16x32_bf16 v[102:105], v[238:241], v[214:217], v[102:105]
	v_mfma_f32_16x16x32_bf16 v[66:69], v[230:233], v[222:225], v[66:69]
	v_mfma_f32_16x16x32_bf16 v[70:73], v[238:241], v[222:225], v[70:73]
	s_setprio 0
	s_mov_b32 m0, s38
	s_barrier
; #define PG8_STAGE(bufoff, gbase) PG8_STAGE_(bufoff, gbase, voffA)
; #define PG8_STAGEB(bufoff, gbase) PG8_STAGE_(bufoff, gbase, voffB)
; #define PG8_LDA(dst, b, h) do { _Pragma("unroll") for (int m = 0; m < 4; ++m) _Pragma("unroll") for (int k = 0; k < 2; ++k) dst[m][k] = *(const LAS bf16x8*)(lds + PG8_SA(b, h) + aoff + m * 2048 + k * 1024); } while (0)
; #define PG8_MMA(ai, bj, At, Bt) do { __builtin_amdgcn_s_setprio(1); _Pragma("unroll") for (int m = 0; m < 4; ++m) _Pragma("unroll") for (int n = 0; n < 2; ++n) _Pragma("unroll") for (int k = 0; k < 2; ++k) \
;         acc[ai][bj][m][n] = __builtin_amdgcn_mfma_f32_16x16x32_bf16(Bt[n][k], At[m][k], acc[ai][bj][m][n], 0, 0, 0); __builtin_amdgcn_s_setprio(0); } while (0)
; #define PG8_WAIT_V(n) asm volatile("s_waitcnt vmcnt(" #n ")" ::: "memory")
; #define PG8_WAIT_L(n) asm volatile("s_waitcnt lgkmcnt(" #n ")" ::: "memory")
; #define PG8_BAR __builtin_amdgcn_s_barrier()
; #define PG8_SCHED __builtin_amdgcn_sched_barrier(0)
; template <class Epi>
; __device__ __forceinline__ void gemm_phase(LAS unsigned char* lds, const Gemm g, const StaticOrder& S, const Epi& E) {
;     ...
;             PG8_LDA(At, 1, 1); PG8_STAGE(PG8_SA(1, 0), a3);
;             PG8_BAR; PG8_WAIT_L(0); PG8_MMA(1, 0, At, B0); PG8_BAR; PG8_SCHED;
;             PG8_STAGEB(PG8_SB(1, 1), b3 + hstep);
;             PG8_WAIT_V(6); PG8_BAR; PG8_MMA(1, 1, At, B1); PG8_BAR;
;     __device__ __forceinline__ void operator()(AccT& acc, const Unit& u, int wr, int wc, int fr, int fq) const {
;         int row0 = u.pm * 256 + wr * 64 + fr, col0 = u.pn * 256 + wc * 32 + 8 * fq;
;         asm volatile("" : "+v"(row0), "+v"(col0));
;         const bool gate = u.pn >= 37;
;         f32x4 bv[2][2];
; #pragma unroll
;         for (int bj = 0; bj < 2; ++bj)
; #pragma unroll
;             for (int n = 0; n < 2; ++n) bv[bj][n] = gate ? *(const f32x4*)(mb + (col0 - GATE0) + bj * 128 + n * 4) : (f32x4){0.f, 0.f, 0.f, 0.f};
	ds_read_b128 v[166:169], v171 offset:49152
	ds_read_b128 v[172:175], v171 offset:50176
	ds_read_b128 v[176:179], v171 offset:51200
	ds_read_b128 v[206:209], v171 offset:52224
	ds_read_b128 v[210:213], v171 offset:53248
	ds_read_b128 v[214:217], v171 offset:54272
	ds_read_b128 v[218:221], v171 offset:55296
	global_load_lds_dwordx4 v160, s[100:101]
	s_mov_b32 m0, s80
	ds_read_b128 v[222:225], v171 offset:56320
	global_load_lds_dwordx4 v158, s[100:101]
	s_barrier
	s_waitcnt lgkmcnt(0)
	s_setprio 1
	v_mfma_f32_16x16x32_bf16 v[58:61], v[74:77], v[166:169], v[58:61]
	v_mfma_f32_16x16x32_bf16 v[62:65], v[90:93], v[166:169], v[62:65]
	s_add_u32 s20, s20, 0x80080
	v_mfma_f32_16x16x32_bf16 v[42:45], v[74:77], v[176:179], v[42:45]
	s_addc_u32 s21, s21, 0
	v_mfma_f32_16x16x32_bf16 v[46:49], v[90:93], v[176:179], v[46:49]
	s_add_i32 s44, s44, s55
	v_mfma_f32_16x16x32_bf16 v[26:29], v[74:77], v[210:213], v[26:29]
	s_mov_b32 m0, s44
	v_mfma_f32_16x16x32_bf16 v[30:33], v[90:93], v[210:213], v[30:33]
	v_mfma_f32_16x16x32_bf16 v[10:13], v[74:77], v[218:221], v[10:13]
	v_mfma_f32_16x16x32_bf16 v[14:17], v[90:93], v[218:221], v[14:17]
	v_mfma_f32_16x16x32_bf16 v[58:61], v[86:89], v[172:175], v[58:61]
	v_mfma_f32_16x16x32_bf16 v[62:65], v[94:97], v[172:175], v[62:65]
	v_mfma_f32_16x16x32_bf16 v[42:45], v[86:89], v[206:209], v[42:45]
	v_mfma_f32_16x16x32_bf16 v[46:49], v[94:97], v[206:209], v[46:49]
	v_mfma_f32_16x16x32_bf16 v[26:29], v[86:89], v[214:217], v[26:29]
	v_mfma_f32_16x16x32_bf16 v[30:33], v[94:97], v[214:217], v[30:33]
	v_mfma_f32_16x16x32_bf16 v[10:13], v[86:89], v[222:225], v[10:13]
	v_mfma_f32_16x16x32_bf16 v[14:17], v[94:97], v[222:225], v[14:17]
	s_setprio 0
	s_barrier
	global_load_lds_dwordx4 v0, s[20:21]
	s_add_i32 m0, s44, 0x2000
	s_nop 0
	global_load_lds_dwordx4 v156, s[20:21]
	s_waitcnt vmcnt(6)
	s_barrier
	s_setprio 1
	v_mfma_f32_16x16x32_bf16 v[50:53], v[226:229], v[166:169], v[50:53]
	s_add_i32 s88, s88, 2
	v_mfma_f32_16x16x32_bf16 v[54:57], v[234:237], v[166:169], v[54:57]
	s_add_u32 s30, s30, 0x100
	v_mfma_f32_16x16x32_bf16 v[34:37], v[226:229], v[176:179], v[34:37]
	s_addc_u32 s31, s31, 0
	v_mfma_f32_16x16x32_bf16 v[38:41], v[234:237], v[176:179], v[38:41]
	s_add_u32 s86, s86, 0x100
	v_mfma_f32_16x16x32_bf16 v[18:21], v[226:229], v[210:213], v[18:21]
	s_addc_u32 s87, s87, 0
	v_mfma_f32_16x16x32_bf16 v[22:25], v[234:237], v[210:213], v[22:25]
	s_add_u32 s20, s30, 0xfff80080
	v_mfma_f32_16x16x32_bf16 v[6:9], v[226:229], v[218:221], v[6:9]
	s_addc_u32 s21, s31, -1
	v_mfma_f32_16x16x32_bf16 v[2:5], v[234:237], v[218:221], v[2:5]
	s_add_i32 s58, 0, 0x10000
	v_mfma_f32_16x16x32_bf16 v[50:53], v[230:233], v[172:175], v[50:53]
	s_cmp_eq_u32 s88, 28
	v_mfma_f32_16x16x32_bf16 v[54:57], v[238:241], v[172:175], v[54:57]
	s_cselect_b32 s45, s35, s21
	v_mfma_f32_16x16x32_bf16 v[34:37], v[230:233], v[206:209], v[34:37]
	s_cselect_b32 s44, s84, s20
	v_mfma_f32_16x16x32_bf16 v[38:41], v[238:241], v[206:209], v[38:41]
	s_cselect_b32 s21, s25, s87
	v_mfma_f32_16x16x32_bf16 v[18:21], v[230:233], v[214:217], v[18:21]
	s_cselect_b32 s20, s85, s86
	v_mfma_f32_16x16x32_bf16 v[22:25], v[238:241], v[214:217], v[22:25]
	s_add_u32 s100, s44, s16
	v_mfma_f32_16x16x32_bf16 v[6:9], v[230:233], v[222:225], v[6:9]
	s_addc_u32 s101, s45, s17
	v_mfma_f32_16x16x32_bf16 v[2:5], v[238:241], v[222:225], v[2:5]
	s_add_i32 m0, s62, 0xc000
	s_setprio 0
	s_cmp_gt_u32 s88, 29
	s_barrier
	s_cbranch_scc0 .LBB0_426
	v_mov_b32_e32 v74, v250
	s_lshl_b32 s21, s83, 8
	v_readfirstlane_b32 s20, v74
	s_ashr_i32 s25, s20, 2
	s_andn2_b32 s25, s25, 63
	s_lshr_b32 s20, s20, 1
	s_add_i32 s25, s25, s21
	s_lshl_b32 s21, s82, 8
	s_and_b32 s20, s20, 0x60
	v_and_or_b32 v172, v74, 15, s25
	s_or_b32 s20, s20, s21
	v_lshrrev_b32_e32 v74, 1, v74
	v_and_or_b32 v166, v74, 24, s20
	s_cmp_gt_i32 s82, 36
	v_ashrrev_i32_e32 v167, 31, v166
	v_mov_b32_e32 v90, 0
	s_cselect_b64 s[20:21], -1, 0
	s_cmp_lt_i32 s82, 37
	v_lshl_add_u64 v[168:169], v[166:167], 2, s[6:7]
	v_mov_b32_e32 v94, 0
	v_mov_b32_e32 v95, v90
	v_mov_b32_e32 v96, 0
	v_mov_b32_e32 v97, 0
	s_cbranch_scc1 .LBB0_429
	v_add_co_u32_e32 v74, vcc, 0xffff7000, v168
	s_nop 1
	v_addc_co_u32_e32 v75, vcc, -1, v169, vcc
	global_load_dwordx4 v[94:97], v[74:75], off offset:-1024

; #define PG8_STAGE(bufoff, gbase) PG8_STAGE_(bufoff, gbase, voffA)
; #define PG8_STAGEB(bufoff, gbase) PG8_STAGE_(bufoff, gbase, voffB)
; #define PG8_LDA(dst, b, h) do { _Pragma("unroll") for (int m = 0; m < 4; ++m) _Pragma("unroll") for (int k = 0; k < 2; ++k) dst[m][k] = *(const LAS bf16x8*)(lds + PG8_SA(b, h) + aoff + m * 2048 + k * 1024); } while (0)
; #define PG8_LDB(dst, b, h) do { _Pragma("unroll") for (int n = 0; n < 2; ++n) _Pragma("unroll") for (int k = 0; k < 2; ++k) dst[n][k] = *(const LAS bf16x8*)(lds + PG8_SB(b, h) + boff + n * 2048 + k * 1024); } while (0)
; #define PG8_MMA(ai, bj, At, Bt) do { __builtin_amdgcn_s_setprio(1); _Pragma("unroll") for (int m = 0; m < 4; ++m) _Pragma("unroll") for (int n = 0; n < 2; ++n) _Pragma("unroll") for (int k = 0; k < 2; ++k) \
;         acc[ai][bj][m][n] = __builtin_amdgcn_mfma_f32_16x16x32_bf16(Bt[n][k], At[m][k], acc[ai][bj][m][n], 0, 0, 0); __builtin_amdgcn_s_setprio(0); } while (0)
; #define PG8_WAIT_V(n) asm volatile("s_waitcnt vmcnt(" #n ")" ::: "memory")
; #define PG8_WAIT_L(n) asm volatile("s_waitcnt lgkmcnt(" #n ")" ::: "memory")
; #define PG8_BAR __builtin_amdgcn_s_barrier()
; #define PG8_SCHED __builtin_amdgcn_sched_barrier(0)
; template <class Epi>
; __device__ __forceinline__ void gemm_phase(LAS unsigned char* lds, const Gemm g, const StaticOrder& S, const Epi& E) {
;     ...
;             PG8_LDB(B0, 0, 0); PG8_SCHED; PG8_LDA(At, 0, 0); PG8_STAGE(PG8_SA(1, 1), a1 + hstep);
;             PG8_WAIT_L(8); PG8_BAR; PG8_WAIT_L(0); PG8_MMA(0, 0, At, B0); PG8_BAR; PG8_SCHED;
;             PG8_LDB(B1, 0, 1); PG8_STAGEB(PG8_SB(0, 0), b2);
;             PG8_BAR; PG8_WAIT_L(0); PG8_MMA(0, 1, At, B1); PG8_BAR;
;             PG8_LDA(At, 0, 1); PG8_STAGE(PG8_SA(0, 0), a2);
;             PG8_BAR; PG8_WAIT_L(0); PG8_MMA(1, 0, At, B0); PG8_BAR; PG8_SCHED;
;             PG8_STAGEB(PG8_SB(0, 1), b2 + hstep);
;             PG8_WAIT_V(6); PG8_BAR; PG8_MMA(1, 1, At, B1); PG8_BAR;
;             PG8_LDB(B0, 1, 0); PG8_SCHED; PG8_LDA(At, 1, 0); PG8_STAGE(PG8_SA(0, 1), a2 + hstep);
;             PG8_WAIT_L(8); PG8_BAR; PG8_WAIT_L(0); PG8_MMA(0, 0, At, B0); PG8_BAR; PG8_SCHED;
.LBB0_1447:
	ds_read_b128 v[144:147], v140
	ds_read_b128 v[148:151], v140 offset:1024
	ds_read_b128 v[152:155], v140 offset:2048
	ds_read_b128 v[156:159], v140 offset:3072
	ds_read_b128 v[160:163], v143
	ds_read_b128 v[164:167], v143 offset:1024
	ds_read_b128 v[168:171], v143 offset:2048
	ds_read_b128 v[172:175], v143 offset:3072
	ds_read_b128 v[176:179], v143 offset:4096
	ds_read_b128 v[188:191], v143 offset:5120
	ds_read_b128 v[192:195], v143 offset:6144
	global_load_lds_dwordx4 v136, s[30:31]
	s_add_i32 m0, s55, 0xe000
	ds_read_b128 v[196:199], v143 offset:7168
	global_load_lds_dwordx4 v138, s[30:31]
	s_waitcnt lgkmcnt(8)
	s_barrier
	s_waitcnt lgkmcnt(0)
	s_setprio 1
	v_mfma_f32_16x16x32_bf16 v[126:129], v[144:147], v[160:163], v[126:129]
	v_mfma_f32_16x16x32_bf16 v[122:125], v[152:155], v[160:163], v[122:125]
	s_add_i32 s89, 0, 0x14000
	v_mfma_f32_16x16x32_bf16 v[110:113], v[144:147], v[168:171], v[110:113]
	s_add_i32 s58, s58, s54
	v_mfma_f32_16x16x32_bf16 v[106:109], v[152:155], v[168:171], v[106:109]
	s_mov_b32 m0, s58
	v_mfma_f32_16x16x32_bf16 v[94:97], v[144:147], v[176:179], v[94:97]
	v_mfma_f32_16x16x32_bf16 v[90:93], v[152:155], v[176:179], v[90:93]
	v_mfma_f32_16x16x32_bf16 v[78:81], v[144:147], v[192:195], v[78:81]
	v_mfma_f32_16x16x32_bf16 v[74:77], v[152:155], v[192:195], v[74:77]
	v_mfma_f32_16x16x32_bf16 v[126:129], v[148:151], v[164:167], v[126:129]
	v_mfma_f32_16x16x32_bf16 v[122:125], v[156:159], v[164:167], v[122:125]
	v_mfma_f32_16x16x32_bf16 v[110:113], v[148:151], v[172:175], v[110:113]
	v_mfma_f32_16x16x32_bf16 v[106:109], v[156:159], v[172:175], v[106:109]
	v_mfma_f32_16x16x32_bf16 v[94:97], v[148:151], v[188:191], v[94:97]
	v_mfma_f32_16x16x32_bf16 v[90:93], v[156:159], v[188:191], v[90:93]
	v_mfma_f32_16x16x32_bf16 v[78:81], v[148:151], v[196:199], v[78:81]
	v_mfma_f32_16x16x32_bf16 v[74:77], v[156:159], v[196:199], v[74:77]
	s_setprio 0
	s_barrier
	ds_read_b128 v[200:203], v141
	ds_read_b128 v[206:209], v141 offset:1024
	ds_read_b128 v[210:213], v141 offset:2048
	global_load_lds_dwordx4 v0, s[20:21]
	s_add_i32 m0, s58, 0x2000
	ds_read_b128 v[214:217], v141 offset:3072
	global_load_lds_dwordx4 v130, s[20:21]
	s_barrier
	s_waitcnt lgkmcnt(0)
	s_setprio 1
	v_mfma_f32_16x16x32_bf16 v[118:121], v[200:203], v[160:163], v[118:121]
	v_mfma_f32_16x16x32_bf16 v[114:117], v[210:213], v[160:163], v[114:117]
	v_mfma_f32_16x16x32_bf16 v[102:105], v[200:203], v[168:171], v[102:105]
	v_mfma_f32_16x16x32_bf16 v[98:101], v[210:213], v[168:171], v[98:101]
	v_mfma_f32_16x16x32_bf16 v[86:89], v[200:203], v[176:179], v[86:89]
	v_mfma_f32_16x16x32_bf16 v[82:85], v[210:213], v[176:179], v[82:85]
	v_mfma_f32_16x16x32_bf16 v[70:73], v[200:203], v[192:195], v[70:73]
	v_mfma_f32_16x16x32_bf16 v[66:69], v[210:213], v[192:195], v[66:69]
	v_mfma_f32_16x16x32_bf16 v[118:121], v[206:209], v[164:167], v[118:121]
	v_mfma_f32_16x16x32_bf16 v[114:117], v[214:217], v[164:167], v[114:117]
	v_mfma_f32_16x16x32_bf16 v[102:105], v[206:209], v[172:175], v[102:105]
	v_mfma_f32_16x16x32_bf16 v[98:101], v[214:217], v[172:175], v[98:101]
	v_mfma_f32_16x16x32_bf16 v[86:89], v[206:209], v[188:191], v[86:89]
	v_mfma_f32_16x16x32_bf16 v[82:85], v[214:217], v[188:191], v[82:85]
	v_mfma_f32_16x16x32_bf16 v[70:73], v[206:209], v[196:199], v[70:73]
	v_mfma_f32_16x16x32_bf16 v[66:69], v[214:217], v[196:199], v[66:69]
	s_setprio 0
	s_mov_b32 m0, s55
	s_barrier
	ds_read_b128 v[160:163], v143 offset:16384
	ds_read_b128 v[164:167], v143 offset:17408
	ds_read_b128 v[168:171], v143 offset:18432
	ds_read_b128 v[172:175], v143 offset:19456
	ds_read_b128 v[176:179], v143 offset:20480
	ds_read_b128 v[188:191], v143 offset:21504
	ds_read_b128 v[192:195], v143 offset:22528
	global_load_lds_dwordx4 v134, s[48:49]
	s_mov_b32 m0, s62
	ds_read_b128 v[196:199], v143 offset:23552
	global_load_lds_dwordx4 v132, s[48:49]
	s_barrier
	s_waitcnt lgkmcnt(0)
	s_setprio 1
	v_mfma_f32_16x16x32_bf16 v[62:65], v[144:147], v[160:163], v[62:65]
	v_mfma_f32_16x16x32_bf16 v[58:61], v[152:155], v[160:163], v[58:61]
	s_add_u32 s58, s20, 0x80000
	v_mfma_f32_16x16x32_bf16 v[46:49], v[144:147], v[168:171], v[46:49]
	s_addc_u32 s59, s21, 0
	v_mfma_f32_16x16x32_bf16 v[42:45], v[152:155], v[168:171], v[42:45]
	s_add_i32 s89, s89, s54
	v_mfma_f32_16x16x32_bf16 v[30:33], v[144:147], v[176:179], v[30:33]
	s_mov_b32 m0, s89
	v_mfma_f32_16x16x32_bf16 v[26:29], v[152:155], v[176:179], v[26:29]
	v_mfma_f32_16x16x32_bf16 v[14:17], v[144:147], v[192:195], v[14:17]
	v_mfma_f32_16x16x32_bf16 v[10:13], v[152:155], v[192:195], v[10:13]
	v_mfma_f32_16x16x32_bf16 v[62:65], v[148:151], v[164:167], v[62:65]
	v_mfma_f32_16x16x32_bf16 v[58:61], v[156:159], v[164:167], v[58:61]
	v_mfma_f32_16x16x32_bf16 v[46:49], v[148:151], v[172:175], v[46:49]
	v_mfma_f32_16x16x32_bf16 v[42:45], v[156:159], v[172:175], v[42:45]
	v_mfma_f32_16x16x32_bf16 v[30:33], v[148:151], v[188:191], v[30:33]
	v_mfma_f32_16x16x32_bf16 v[26:29], v[156:159], v[188:191], v[26:29]
	v_mfma_f32_16x16x32_bf16 v[14:17], v[148:151], v[196:199], v[14:17]
	v_mfma_f32_16x16x32_bf16 v[10:13], v[156:159], v[196:199], v[10:13]
	s_setprio 0
	s_barrier
	global_load_lds_dwordx4 v0, s[58:59]
	s_add_i32 m0, s89, 0x2000
	s_nop 0
	global_load_lds_dwordx4 v130, s[58:59]
	s_waitcnt vmcnt(6)
	s_barrier
; #define PG8_STAGE(bufoff, gbase) PG8_STAGE_(bufoff, gbase, voffA)
; #define PG8_STAGEB(bufoff, gbase) PG8_STAGE_(bufoff, gbase, voffB)
; #define PG8_LDA(dst, b, h) do { _Pragma("unroll") for (int m = 0; m < 4; ++m) _Pragma("unroll") for (int k = 0; k < 2; ++k) dst[m][k] = *(const LAS bf16x8*)(lds + PG8_SA(b, h) + aoff + m * 2048 + k * 1024); } while (0)
; #define PG8_LDB(dst, b, h) do { _Pragma("unroll") for (int n = 0; n < 2; ++n) _Pragma("unroll") for (int k = 0; k < 2; ++k) dst[n][k] = *(const LAS bf16x8*)(lds + PG8_SB(b, h) + boff + n * 2048 + k * 1024); } while (0)
; #define PG8_MMA(ai, bj, At, Bt) do { __builtin_amdgcn_s_setprio(1); _Pragma("unroll") for (int m = 0; m < 4; ++m) _Pragma("unroll") for (int n = 0; n < 2; ++n) _Pragma("unroll") for (int k = 0; k < 2; ++k) \
;         acc[ai][bj][m][n] = __builtin_amdgcn_mfma_f32_16x16x32_bf16(Bt[n][k], At[m][k], acc[ai][bj][m][n], 0, 0, 0); __builtin_amdgcn_s_setprio(0); } while (0)
; #define PG8_WAIT_V(n) asm volatile("s_waitcnt vmcnt(" #n ")" ::: "memory")
; #define PG8_WAIT_L(n) asm volatile("s_waitcnt lgkmcnt(" #n ")" ::: "memory")
; #define PG8_BAR __builtin_amdgcn_s_barrier()
; #define PG8_SCHED __builtin_amdgcn_sched_barrier(0)
; template <class Epi>
; __device__ __forceinline__ void gemm_phase(LAS unsigned char* lds, const Gemm g, const StaticOrder& S, const Epi& E) {
;     ...
;             PG8_BAR; PG8_WAIT_L(0); PG8_MMA(0, 1, At, B1); PG8_BAR;
;             PG8_LDA(At, 0, 1); PG8_STAGE(PG8_SA(0, 0), a2);
;             PG8_BAR; PG8_WAIT_L(0); PG8_MMA(1, 0, At, B0); PG8_BAR; PG8_SCHED;
;             PG8_STAGEB(PG8_SB(0, 1), b2 + hstep);
;             PG8_WAIT_V(6); PG8_BAR; PG8_MMA(1, 1, At, B1); PG8_BAR;
;             PG8_LDB(B0, 1, 0); PG8_SCHED; PG8_LDA(At, 1, 0); PG8_STAGE(PG8_SA(0, 1), a2 + hstep);
;             PG8_WAIT_L(8); PG8_BAR; PG8_WAIT_L(0); PG8_MMA(0, 0, At, B0); PG8_BAR; PG8_SCHED;
;             PG8_LDB(B1, 1, 1); PG8_STAGEB(PG8_SB(1, 0), b3);
;             PG8_BAR; PG8_WAIT_L(0); PG8_MMA(0, 1, At, B1); PG8_BAR;
;             PG8_LDA(At, 1, 1); PG8_STAGE(PG8_SA(1, 0), a3);
;             PG8_BAR; PG8_WAIT_L(0); PG8_MMA(1, 0, At, B0); PG8_BAR; PG8_SCHED;
;             PG8_STAGEB(PG8_SB(1, 1), b3 + hstep);
;             PG8_WAIT_V(6); PG8_BAR; PG8_MMA(1, 1, At, B1); PG8_BAR;
	s_setprio 1
	v_mfma_f32_16x16x32_bf16 v[54:57], v[200:203], v[160:163], v[54:57]
	v_mfma_f32_16x16x32_bf16 v[50:53], v[210:213], v[160:163], v[50:53]
	s_add_i32 s58, 0, 0x18000
	v_mfma_f32_16x16x32_bf16 v[38:41], v[200:203], v[168:171], v[38:41]
	s_add_u32 s48, s48, 0x80000
	v_mfma_f32_16x16x32_bf16 v[34:37], v[210:213], v[168:171], v[34:37]
	s_addc_u32 s49, s49, 0
	v_mfma_f32_16x16x32_bf16 v[22:25], v[200:203], v[176:179], v[22:25]
	s_mov_b32 m0, s63
	v_mfma_f32_16x16x32_bf16 v[18:21], v[210:213], v[176:179], v[18:21]
	v_mfma_f32_16x16x32_bf16 v[6:9], v[200:203], v[192:195], v[6:9]
	v_mfma_f32_16x16x32_bf16 v[2:5], v[210:213], v[192:195], v[2:5]
	v_mfma_f32_16x16x32_bf16 v[54:57], v[206:209], v[164:167], v[54:57]
	v_mfma_f32_16x16x32_bf16 v[50:53], v[214:217], v[164:167], v[50:53]
	v_mfma_f32_16x16x32_bf16 v[38:41], v[206:209], v[172:175], v[38:41]
	v_mfma_f32_16x16x32_bf16 v[34:37], v[214:217], v[172:175], v[34:37]
	v_mfma_f32_16x16x32_bf16 v[22:25], v[206:209], v[188:191], v[22:25]
	v_mfma_f32_16x16x32_bf16 v[18:21], v[214:217], v[188:191], v[18:21]
	v_mfma_f32_16x16x32_bf16 v[6:9], v[206:209], v[196:199], v[6:9]
	v_mfma_f32_16x16x32_bf16 v[2:5], v[214:217], v[196:199], v[2:5]
	s_setprio 0
	s_barrier
	ds_read_b128 v[144:147], v182
	ds_read_b128 v[148:151], v182 offset:1024
	ds_read_b128 v[152:155], v182 offset:2048
	ds_read_b128 v[156:159], v182 offset:3072
	ds_read_b128 v[160:163], v143 offset:32768
	ds_read_b128 v[164:167], v143 offset:33792
	ds_read_b128 v[168:171], v143 offset:34816
	ds_read_b128 v[172:175], v143 offset:35840
	ds_read_b128 v[176:179], v143 offset:36864
	ds_read_b128 v[188:191], v143 offset:37888
	ds_read_b128 v[192:195], v143 offset:38912
	global_load_lds_dwordx4 v134, s[48:49]
	s_mov_b32 m0, s66
	ds_read_b128 v[196:199], v143 offset:39936
	global_load_lds_dwordx4 v132, s[48:49]
	s_waitcnt lgkmcnt(8)
	s_barrier
	s_waitcnt lgkmcnt(0)
	s_setprio 1
	v_mfma_f32_16x16x32_bf16 v[126:129], v[144:147], v[160:163], v[126:129]
	v_mfma_f32_16x16x32_bf16 v[122:125], v[152:155], v[160:163], v[122:125]
	s_add_i32 s48, 0, 0x1c000
	v_mfma_f32_16x16x32_bf16 v[110:113], v[144:147], v[168:171], v[110:113]
	s_add_i32 s49, s58, s54
	v_mfma_f32_16x16x32_bf16 v[106:109], v[152:155], v[168:171], v[106:109]
	s_add_i32 m0, s49, 0xffffff80
	v_mfma_f32_16x16x32_bf16 v[94:97], v[144:147], v[176:179], v[94:97]
	v_mfma_f32_16x16x32_bf16 v[90:93], v[152:155], v[176:179], v[90:93]
	v_mfma_f32_16x16x32_bf16 v[78:81], v[144:147], v[192:195], v[78:81]
	v_mfma_f32_16x16x32_bf16 v[74:77], v[152:155], v[192:195], v[74:77]
	v_mfma_f32_16x16x32_bf16 v[126:129], v[148:151], v[164:167], v[126:129]
	v_mfma_f32_16x16x32_bf16 v[122:125], v[156:159], v[164:167], v[122:125]
	v_mfma_f32_16x16x32_bf16 v[110:113], v[148:151], v[172:175], v[110:113]
	v_mfma_f32_16x16x32_bf16 v[106:109], v[156:159], v[172:175], v[106:109]
	v_mfma_f32_16x16x32_bf16 v[94:97], v[148:151], v[188:191], v[94:97]
	v_mfma_f32_16x16x32_bf16 v[90:93], v[156:159], v[188:191], v[90:93]
	v_mfma_f32_16x16x32_bf16 v[78:81], v[148:151], v[196:199], v[78:81]
	v_mfma_f32_16x16x32_bf16 v[74:77], v[156:159], v[196:199], v[74:77]
	s_setprio 0
	s_barrier
	ds_read_b128 v[200:203], v183
	ds_read_b128 v[206:209], v183 offset:1024
	ds_read_b128 v[210:213], v183 offset:2048
	global_load_lds_dwordx4 v0, s[20:21] offset:128
	s_add_i32 m0, s49, 0x1f80
	ds_read_b128 v[214:217], v183 offset:3072
	global_load_lds_dwordx4 v130, s[20:21] offset:128
	s_barrier
	s_waitcnt lgkmcnt(0)
	s_setprio 1
	v_mfma_f32_16x16x32_bf16 v[118:121], v[200:203], v[160:163], v[118:121]
	v_mfma_f32_16x16x32_bf16 v[114:117], v[210:213], v[160:163], v[114:117]
	v_mfma_f32_16x16x32_bf16 v[102:105], v[200:203], v[168:171], v[102:105]
	v_mfma_f32_16x16x32_bf16 v[98:101], v[210:213], v[168:171], v[98:101]
	v_mfma_f32_16x16x32_bf16 v[86:89], v[200:203], v[176:179], v[86:89]
	v_mfma_f32_16x16x32_bf16 v[82:85], v[210:213], v[176:179], v[82:85]
	v_mfma_f32_16x16x32_bf16 v[70:73], v[200:203], v[192:195], v[70:73]
	v_mfma_f32_16x16x32_bf16 v[66:69], v[210:213], v[192:195], v[66:69]
	v_mfma_f32_16x16x32_bf16 v[118:121], v[206:209], v[164:167], v[118:121]
	v_mfma_f32_16x16x32_bf16 v[114:117], v[214:217], v[164:167], v[114:117]
	v_mfma_f32_16x16x32_bf16 v[102:105], v[206:209], v[172:175], v[102:105]
	v_mfma_f32_16x16x32_bf16 v[98:101], v[214:217], v[172:175], v[98:101]
	v_mfma_f32_16x16x32_bf16 v[86:89], v[206:209], v[188:191], v[86:89]
	v_mfma_f32_16x16x32_bf16 v[82:85], v[214:217], v[188:191], v[82:85]
	v_mfma_f32_16x16x32_bf16 v[70:73], v[206:209], v[196:199], v[70:73]
	v_mfma_f32_16x16x32_bf16 v[66:69], v[214:217], v[196:199], v[66:69]
	s_setprio 0
	s_mov_b32 m0, s67
	s_barrier
	ds_read_b128 v[160:163], v143 offset:49152
	ds_read_b128 v[164:167], v143 offset:50176
	ds_read_b128 v[168:171], v143 offset:51200
	ds_read_b128 v[172:175], v143 offset:52224
	ds_read_b128 v[176:179], v143 offset:53248
	ds_read_b128 v[188:191], v143 offset:54272
	ds_read_b128 v[192:195], v143 offset:55296
	global_load_lds_dwordx4 v134, s[100:101]
	s_mov_b32 m0, s80
	ds_read_b128 v[196:199], v143 offset:56320
	global_load_lds_dwordx4 v132, s[100:101]
	s_barrier
; __device__ __forceinline__ int fresh_tid() { int t = threadIdx.x; asm volatile("" : "+v"(t)); return t; }
; #define PG8_STAGEB(bufoff, gbase) PG8_STAGE_(bufoff, gbase, voffB)
; #define PG8_MMA(ai, bj, At, Bt) do { __builtin_amdgcn_s_setprio(1); _Pragma("unroll") for (int m = 0; m < 4; ++m) _Pragma("unroll") for (int n = 0; n < 2; ++n) _Pragma("unroll") for (int k = 0; k < 2; ++k) \
;         acc[ai][bj][m][n] = __builtin_amdgcn_mfma_f32_16x16x32_bf16(Bt[n][k], At[m][k], acc[ai][bj][m][n], 0, 0, 0); __builtin_amdgcn_s_setprio(0); } while (0)
; #define PG8_WAIT_V(n) asm volatile("s_waitcnt vmcnt(" #n ")" ::: "memory")
; #define PG8_WAIT_L(n) asm volatile("s_waitcnt lgkmcnt(" #n ")" ::: "memory")
; #define PG8_BAR __builtin_amdgcn_s_barrier()
; #define PG8_SCHED __builtin_amdgcn_sched_barrier(0)
; template <class Epi>
; __device__ __forceinline__ void gemm_phase(LAS unsigned char* lds, const Gemm g, const StaticOrder& S, const Epi& E) {
;     ...
;             PG8_BAR; PG8_WAIT_L(0); PG8_MMA(1, 0, At, B0); PG8_BAR; PG8_SCHED;
;             PG8_STAGEB(PG8_SB(1, 1), b3 + hstep);
;             PG8_WAIT_V(6); PG8_BAR; PG8_MMA(1, 1, At, B1); PG8_BAR;
;         }
;         { const int t2 = fresh_tid(); const int w2 = __builtin_amdgcn_readfirstlane(t2 >> 6); E(acc, cur, w2 >> 2, w2 & 3, t2 & 15, (t2 >> 4) & 3); }
;         if (!has_next) break;
;     __device__ __forceinline__ void operator()(AccT& acc, const Unit& u, int wr, int wc, int fr, int fq) const {
;         int row0 = u.pm * 256 + wr * 64 + fr, col0 = u.pn * 256 + wc * 32 + 8 * fq;
;         asm volatile("" : "+v"(row0), "+v"(col0));
; #pragma unroll
;         for (int ai = 0; ai < 2; ++ai)
; #pragma unroll
;             for (int m = 0; m < 4; ++m) { const size_t off = (size_t)(row0 + ai * 128 + m * 16) * DM + col0;
; #pragma unroll
;                 for (int bj = 0; bj < 2; ++bj) { const f32x4 x0 = *(const f32x4*)(xin + off + bj * 128), x1 = *(const f32x4*)(xin + off + bj * 128 + 4);
;                     __builtin_nontemporal_store(x0 + acc[ai][bj][m][0], (f32x4*)(out + off + bj * 128)); __builtin_nontemporal_store(x1 + acc[ai][bj][m][1], (f32x4*)(out + off + bj * 128 + 4)); } }
	s_waitcnt lgkmcnt(0)
	s_setprio 1
	v_mfma_f32_16x16x32_bf16 v[62:65], v[144:147], v[160:163], v[62:65]
	v_mfma_f32_16x16x32_bf16 v[58:61], v[152:155], v[160:163], v[58:61]
	s_add_u32 s20, s20, 0x80080
	v_mfma_f32_16x16x32_bf16 v[46:49], v[144:147], v[168:171], v[46:49]
	s_addc_u32 s21, s21, 0
	v_mfma_f32_16x16x32_bf16 v[42:45], v[152:155], v[168:171], v[42:45]
	s_add_i32 s48, s48, s54
	v_mfma_f32_16x16x32_bf16 v[30:33], v[144:147], v[176:179], v[30:33]
	s_mov_b32 m0, s48
	v_mfma_f32_16x16x32_bf16 v[26:29], v[152:155], v[176:179], v[26:29]
	v_mfma_f32_16x16x32_bf16 v[14:17], v[144:147], v[192:195], v[14:17]
	v_mfma_f32_16x16x32_bf16 v[10:13], v[152:155], v[192:195], v[10:13]
	v_mfma_f32_16x16x32_bf16 v[62:65], v[148:151], v[164:167], v[62:65]
	v_mfma_f32_16x16x32_bf16 v[58:61], v[156:159], v[164:167], v[58:61]
	v_mfma_f32_16x16x32_bf16 v[46:49], v[148:151], v[172:175], v[46:49]
	v_mfma_f32_16x16x32_bf16 v[42:45], v[156:159], v[172:175], v[42:45]
	v_mfma_f32_16x16x32_bf16 v[30:33], v[148:151], v[188:191], v[30:33]
	v_mfma_f32_16x16x32_bf16 v[26:29], v[156:159], v[188:191], v[26:29]
	v_mfma_f32_16x16x32_bf16 v[14:17], v[148:151], v[196:199], v[14:17]
	v_mfma_f32_16x16x32_bf16 v[10:13], v[156:159], v[196:199], v[10:13]
	s_setprio 0
	s_barrier
	global_load_lds_dwordx4 v0, s[20:21]
	s_add_i32 m0, s48, 0x2000
	s_nop 0
	global_load_lds_dwordx4 v130, s[20:21]
	s_waitcnt vmcnt(6)
	s_barrier
	s_setprio 1
	v_mfma_f32_16x16x32_bf16 v[54:57], v[200:203], v[160:163], v[54:57]
	s_add_i32 s88, s88, 2
	v_mfma_f32_16x16x32_bf16 v[50:53], v[210:213], v[160:163], v[50:53]
	s_add_u32 s30, s30, 0x100
	v_mfma_f32_16x16x32_bf16 v[38:41], v[200:203], v[168:171], v[38:41]
	s_addc_u32 s31, s31, 0
	v_mfma_f32_16x16x32_bf16 v[34:37], v[210:213], v[168:171], v[34:37]
	s_add_u32 s86, s86, 0x100
	v_mfma_f32_16x16x32_bf16 v[22:25], v[200:203], v[176:179], v[22:25]
	s_addc_u32 s87, s87, 0
	v_mfma_f32_16x16x32_bf16 v[18:21], v[210:213], v[176:179], v[18:21]
	s_add_u32 s20, s30, 0xfff80080
	v_mfma_f32_16x16x32_bf16 v[6:9], v[200:203], v[192:195], v[6:9]
	s_addc_u32 s21, s31, -1
	v_mfma_f32_16x16x32_bf16 v[2:5], v[210:213], v[192:195], v[2:5]
	s_add_i32 s58, 0, 0x10000
	v_mfma_f32_16x16x32_bf16 v[54:57], v[206:209], v[164:167], v[54:57]
	s_cmp_eq_u32 s88, 28
	v_mfma_f32_16x16x32_bf16 v[50:53], v[214:217], v[164:167], v[50:53]
	s_cselect_b32 s49, s25, s21
	v_mfma_f32_16x16x32_bf16 v[38:41], v[206:209], v[172:175], v[38:41]
	s_cselect_b32 s48, s84, s20
	v_mfma_f32_16x16x32_bf16 v[34:37], v[214:217], v[172:175], v[34:37]
	s_cselect_b32 s21, s7, s87
	v_mfma_f32_16x16x32_bf16 v[22:25], v[206:209], v[188:191], v[22:25]
	s_cselect_b32 s20, s85, s86
	v_mfma_f32_16x16x32_bf16 v[18:21], v[214:217], v[188:191], v[18:21]
	s_add_u32 s100, s48, s16
	v_mfma_f32_16x16x32_bf16 v[6:9], v[206:209], v[196:199], v[6:9]
	s_addc_u32 s101, s49, s17
	v_mfma_f32_16x16x32_bf16 v[2:5], v[214:217], v[196:199], v[2:5]
	s_add_i32 m0, s55, 0xc000
	s_setprio 0
	s_cmp_gt_u32 s88, 29
	s_barrier
	s_cbranch_scc0 .LBB0_1447
	v_mov_b32_e32 v141, v250
	s_lshl_b32 s20, s83, 8
	v_readfirstlane_b32 s7, v141
	s_ashr_i32 s21, s7, 2
	s_andn2_b32 s21, s21, 63
	s_lshr_b32 s7, s7, 1
	s_add_i32 s21, s21, s20
	s_lshl_b32 s20, s82, 8
	s_and_b32 s7, s7, 0x60
	v_and_or_b32 v140, v141, 15, s21
	s_or_b32 s7, s7, s20
	v_lshrrev_b32_e32 v141, 1, v141
	v_and_or_b32 v144, v141, 24, s7
	s_mov_b64 s[20:21], 0x20000
	v_ashrrev_i32_e32 v141, 31, v140
	v_ashrrev_i32_e32 v145, 31, v144
	v_lshlrev_b64 v[140:141], 11, v[140:141]
	v_lshl_add_u64 v[140:141], v[140:141], 0, v[144:145]
	v_lshlrev_b64 v[140:141], 2, v[140:141]
	v_lshl_add_u64 v[152:153], s[0:1], 0, v[140:141]
	global_load_dwordx4 v[144:147], v[152:153], off offset:16
	global_load_dwordx4 v[148:151], v[152:153], off
	s_and_b64 vcc, exec, s[42:43]
	s_mov_b32 s82, s6
	s_mov_b32 s83, s24
	s_mov_b64 s[30:31], s[34:35]
	s_mov_b32 s86, 0x3fb8aa3b
	s_mov_b32 s89, 0x42b17218
	s_waitcnt vmcnt(0)
	v_pk_add_f32 v[124:125], v[124:125], v[146:147]
	v_pk_add_f32 v[128:129], v[128:129], v[150:151]
	v_pk_add_f32 v[126:127], v[126:127], v[148:149]
	v_lshl_add_u64 v[148:149], s[44:45], 0, v[140:141]
	v_pk_add_f32 v[122:123], v[122:123], v[144:145]
	global_store_dwordx4 v[148:149], v[126:129], off nt
	global_store_dwordx4 v[148:149], v[122:125], off offset:16 nt
	global_load_dwordx4 v[122:125], v[152:153], off offset:528
	s_nop 0
	global_load_dwordx4 v[126:129], v[152:153], off offset:512
	s_waitcnt vmcnt(0)
	v_pk_add_f32 v[116:117], v[116:117], v[124:125]
	v_pk_add_f32 v[120:121], v[120:121], v[128:129]
	v_pk_add_f32 v[118:119], v[118:119], v[126:127]
	v_pk_add_f32 v[114:115], v[114:115], v[122:123]
	v_lshl_add_u64 v[122:123], v[140:141], 0, s[20:21]
	global_store_dwordx4 v[148:149], v[118:121], off offset:512 nt
	global_store_dwordx4 v[148:149], v[114:117], off offset:528 nt
	v_lshl_add_u64 v[124:125], s[0:1], 0, v[122:123]
	global_load_dwordx4 v[114:117], v[124:125], off offset:16
	global_load_dwordx4 v[118:121], v[124:125], off
	s_mov_b64 s[20:21], 0x40000
	s_waitcnt vmcnt(0)
	v_pk_add_f32 v[108:109], v[108:109], v[116:117]
	v_pk_add_f32 v[112:113], v[112:113], v[120:121]
	v_pk_add_f32 v[110:111], v[110:111], v[118:119]
	v_lshl_add_u64 v[118:119], s[44:45], 0, v[122:123]
	v_pk_add_f32 v[106:107], v[106:107], v[114:115]
	global_store_dwordx4 v[118:119], v[110:113], off nt
	global_store_dwordx4 v[118:119], v[106:109], off offset:16 nt
	global_load_dwordx4 v[106:109], v[124:125], off offset:528
	s_nop 0
	global_load_dwordx4 v[110:113], v[124:125], off offset:512
	s_waitcnt vmcnt(0)
; __device__ __forceinline__ int fresh_tid() { int t = threadIdx.x; asm volatile("" : "+v"(t)); return t; }
; #define PG8_WAIT_V(n) asm volatile("s_waitcnt vmcnt(" #n ")" ::: "memory")
; #define PG8_BAR __builtin_amdgcn_s_barrier()
; template <class Epi>
; __device__ __forceinline__ void gemm_phase(LAS unsigned char* lds, const Gemm g, const StaticOrder& S, const Epi& E) {
;     ...
;         { const int t2 = fresh_tid(); const int w2 = __builtin_amdgcn_readfirstlane(t2 >> 6); E(acc, cur, w2 >> 2, w2 & 3, t2 & 15, (t2 >> 4) & 3); }
;         if (!has_next) break;
; #pragma unroll
;         for (int a = 0; a < 2; ++a)
; #pragma unroll
;             for (int b = 0; b < 2; ++b)
; #pragma unroll
;                 for (int m = 0; m < 4; ++m)
; #pragma unroll
;                     for (int n = 0; n < 2; ++n) acc[a][b][m][n] = (f32x4){0.f, 0.f, 0.f, 0.f};
;         cur = nxt; cA = nA; cB = nB; ++ui;
;     }
;     PG8_WAIT_V(0);
;     if (wr == 0) PG8_BAR;
;     PG8_BAR;
;     __device__ __forceinline__ void operator()(AccT& acc, const Unit& u, int wr, int wc, int fr, int fq) const {
;     ...
; #pragma unroll
;         for (int ai = 0; ai < 2; ++ai)
; #pragma unroll
;             for (int m = 0; m < 4; ++m) { const size_t off = (size_t)(row0 + ai * 128 + m * 16) * DM + col0;
; #pragma unroll
;                 for (int bj = 0; bj < 2; ++bj) { const f32x4 x0 = *(const f32x4*)(xin + off + bj * 128), x1 = *(const f32x4*)(xin + off + bj * 128 + 4);
;                     __builtin_nontemporal_store(x0 + acc[ai][bj][m][0], (f32x4*)(out + off + bj * 128)); __builtin_nontemporal_store(x1 + acc[ai][bj][m][1], (f32x4*)(out + off + bj * 128 + 4)); } }
;     }
	v_pk_add_f32 v[100:101], v[100:101], v[108:109]
	v_pk_add_f32 v[104:105], v[104:105], v[112:113]
	v_pk_add_f32 v[102:103], v[102:103], v[110:111]
	v_pk_add_f32 v[98:99], v[98:99], v[106:107]
	v_lshl_add_u64 v[106:107], v[140:141], 0, s[20:21]
	global_store_dwordx4 v[118:119], v[102:105], off offset:512 nt
	global_store_dwordx4 v[118:119], v[98:101], off offset:528 nt
	v_lshl_add_u64 v[108:109], s[0:1], 0, v[106:107]
	global_load_dwordx4 v[98:101], v[108:109], off offset:16
	global_load_dwordx4 v[102:105], v[108:109], off
	s_mov_b64 s[20:21], 0x60000
	s_waitcnt vmcnt(0)
	v_pk_add_f32 v[92:93], v[92:93], v[100:101]
	v_pk_add_f32 v[96:97], v[96:97], v[104:105]
	v_pk_add_f32 v[94:95], v[94:95], v[102:103]
	v_lshl_add_u64 v[102:103], s[44:45], 0, v[106:107]
	v_pk_add_f32 v[90:91], v[90:91], v[98:99]
	global_store_dwordx4 v[102:103], v[94:97], off nt
	global_store_dwordx4 v[102:103], v[90:93], off offset:16 nt
	global_load_dwordx4 v[90:93], v[108:109], off offset:528
	s_nop 0
	global_load_dwordx4 v[94:97], v[108:109], off offset:512
	s_waitcnt vmcnt(0)
	v_pk_add_f32 v[84:85], v[84:85], v[92:93]
	v_pk_add_f32 v[88:89], v[88:89], v[96:97]
	v_pk_add_f32 v[86:87], v[86:87], v[94:95]
	v_pk_add_f32 v[82:83], v[82:83], v[90:91]
	v_lshl_add_u64 v[90:91], v[140:141], 0, s[20:21]
	global_store_dwordx4 v[102:103], v[86:89], off offset:512 nt
	global_store_dwordx4 v[102:103], v[82:85], off offset:528 nt
	v_lshl_add_u64 v[92:93], s[0:1], 0, v[90:91]
	global_load_dwordx4 v[82:85], v[92:93], off offset:16
	global_load_dwordx4 v[86:89], v[92:93], off
	s_mov_b64 s[20:21], 0x100000
	s_waitcnt vmcnt(0)
	v_pk_add_f32 v[76:77], v[76:77], v[84:85]
	v_pk_add_f32 v[80:81], v[80:81], v[88:89]
	v_pk_add_f32 v[78:79], v[78:79], v[86:87]
	v_lshl_add_u64 v[86:87], s[44:45], 0, v[90:91]
	v_pk_add_f32 v[74:75], v[74:75], v[82:83]
	global_store_dwordx4 v[86:87], v[78:81], off nt
	global_store_dwordx4 v[86:87], v[74:77], off offset:16 nt
	global_load_dwordx4 v[74:77], v[92:93], off offset:528
	s_nop 0
	global_load_dwordx4 v[78:81], v[92:93], off offset:512
	s_waitcnt vmcnt(0)
	v_pk_add_f32 v[68:69], v[68:69], v[76:77]
	v_pk_add_f32 v[72:73], v[72:73], v[80:81]
	v_pk_add_f32 v[70:71], v[70:71], v[78:79]
	v_pk_add_f32 v[66:67], v[66:67], v[74:75]
	v_lshl_add_u64 v[74:75], v[140:141], 0, s[20:21]
	global_store_dwordx4 v[86:87], v[70:73], off offset:512 nt
	global_store_dwordx4 v[86:87], v[66:69], off offset:528 nt
	v_lshl_add_u64 v[76:77], s[0:1], 0, v[74:75]
	global_load_dwordx4 v[66:69], v[76:77], off offset:16
	global_load_dwordx4 v[70:73], v[76:77], off
	s_mov_b64 s[20:21], 0x120000
	s_waitcnt vmcnt(0)
	v_pk_add_f32 v[60:61], v[60:61], v[68:69]
	v_pk_add_f32 v[64:65], v[64:65], v[72:73]
	v_pk_add_f32 v[62:63], v[62:63], v[70:71]
	v_lshl_add_u64 v[70:71], s[44:45], 0, v[74:75]
	v_pk_add_f32 v[58:59], v[58:59], v[66:67]
	global_store_dwordx4 v[70:71], v[62:65], off nt
	global_store_dwordx4 v[70:71], v[58:61], off offset:16 nt
	global_load_dwordx4 v[58:61], v[76:77], off offset:528
	s_nop 0
	global_load_dwordx4 v[62:65], v[76:77], off offset:512
	s_waitcnt vmcnt(0)
	v_pk_add_f32 v[52:53], v[52:53], v[60:61]
	v_pk_add_f32 v[56:57], v[56:57], v[64:65]
	v_pk_add_f32 v[54:55], v[54:55], v[62:63]
	v_pk_add_f32 v[50:51], v[50:51], v[58:59]
	v_lshl_add_u64 v[58:59], v[140:141], 0, s[20:21]
	global_store_dwordx4 v[70:71], v[54:57], off offset:512 nt
	global_store_dwordx4 v[70:71], v[50:53], off offset:528 nt
	v_lshl_add_u64 v[60:61], s[0:1], 0, v[58:59]
	global_load_dwordx4 v[50:53], v[60:61], off offset:16
	global_load_dwordx4 v[54:57], v[60:61], off
	s_mov_b64 s[20:21], 0x140000
	s_waitcnt vmcnt(0)
	v_pk_add_f32 v[44:45], v[44:45], v[52:53]
	v_pk_add_f32 v[48:49], v[48:49], v[56:57]
	v_pk_add_f32 v[46:47], v[46:47], v[54:55]
	v_lshl_add_u64 v[54:55], s[44:45], 0, v[58:59]
	v_pk_add_f32 v[42:43], v[42:43], v[50:51]
	global_store_dwordx4 v[54:55], v[46:49], off nt
	global_store_dwordx4 v[54:55], v[42:45], off offset:16 nt
	global_load_dwordx4 v[42:45], v[60:61], off offset:528
	s_nop 0
	global_load_dwordx4 v[46:49], v[60:61], off offset:512
	s_waitcnt vmcnt(0)
	v_pk_add_f32 v[36:37], v[36:37], v[44:45]
	v_pk_add_f32 v[40:41], v[40:41], v[48:49]
	v_pk_add_f32 v[38:39], v[38:39], v[46:47]
	v_pk_add_f32 v[34:35], v[34:35], v[42:43]
	v_lshl_add_u64 v[42:43], v[140:141], 0, s[20:21]
	global_store_dwordx4 v[54:55], v[38:41], off offset:512 nt
	global_store_dwordx4 v[54:55], v[34:37], off offset:528 nt
	v_lshl_add_u64 v[44:45], s[0:1], 0, v[42:43]
	global_load_dwordx4 v[34:37], v[44:45], off offset:16
	global_load_dwordx4 v[38:41], v[44:45], off
	s_mov_b64 s[20:21], 0x160000
	s_waitcnt vmcnt(0)
	v_pk_add_f32 v[28:29], v[28:29], v[36:37]
	v_pk_add_f32 v[32:33], v[32:33], v[40:41]
	v_pk_add_f32 v[30:31], v[30:31], v[38:39]
	v_lshl_add_u64 v[38:39], s[44:45], 0, v[42:43]
	v_pk_add_f32 v[26:27], v[26:27], v[34:35]
	global_store_dwordx4 v[38:39], v[30:33], off nt
	global_store_dwordx4 v[38:39], v[26:29], off offset:16 nt
	global_load_dwordx4 v[26:29], v[44:45], off offset:528
	s_nop 0
	global_load_dwordx4 v[30:33], v[44:45], off offset:512
	s_waitcnt vmcnt(0)
	v_pk_add_f32 v[20:21], v[20:21], v[28:29]
	v_pk_add_f32 v[24:25], v[24:25], v[32:33]
	v_pk_add_f32 v[22:23], v[22:23], v[30:31]
	v_pk_add_f32 v[18:19], v[18:19], v[26:27]
	v_lshl_add_u64 v[26:27], v[140:141], 0, s[20:21]
	global_store_dwordx4 v[38:39], v[22:25], off offset:512 nt
	global_store_dwordx4 v[38:39], v[18:21], off offset:528 nt
	v_lshl_add_u64 v[28:29], s[0:1], 0, v[26:27]
	global_load_dwordx4 v[18:21], v[28:29], off offset:16
	global_load_dwordx4 v[22:25], v[28:29], off
	s_mov_b64 s[20:21], s[46:47]
	s_waitcnt vmcnt(0)
	v_pk_add_f32 v[12:13], v[12:13], v[20:21]
	v_pk_add_f32 v[16:17], v[16:17], v[24:25]
	v_pk_add_f32 v[14:15], v[14:15], v[22:23]
	v_lshl_add_u64 v[22:23], s[44:45], 0, v[26:27]
	v_pk_add_f32 v[10:11], v[10:11], v[18:19]
	global_store_dwordx4 v[22:23], v[14:17], off nt
	global_store_dwordx4 v[22:23], v[10:13], off offset:16 nt
	global_load_dwordx4 v[10:13], v[28:29], off offset:528
	s_nop 0
	global_load_dwordx4 v[14:17], v[28:29], off offset:512
	s_waitcnt vmcnt(0)
	v_pk_add_f32 v[4:5], v[4:5], v[12:13]
	v_pk_add_f32 v[8:9], v[8:9], v[16:17]
	v_pk_add_f32 v[6:7], v[6:7], v[14:15]
	v_pk_add_f32 v[2:3], v[2:3], v[10:11]
	global_store_dwordx4 v[22:23], v[6:9], off offset:512 nt
	global_store_dwordx4 v[22:23], v[2:5], off offset:528 nt
	s_cbranch_vccz .LBB0_1440
	s_waitcnt vmcnt(0)
	s_cmpk_gt_u32 s38, 0xff
	s_cbranch_scc1 .LBB0_1451
	s_barrier
